# v9 + removed the compiler's vmcnt(0) drain at each GEMM unit start (stores drain under the next K-loop)
# baseline (speedup 1.0000x reference)
; template <class Epi, class Sched, bool ALIGN_EPI = false, bool SP2 = false>
; __device__ __forceinline__ void gemm_phase(PG8_LAS unsigned char* lds, const int tid, const Gemm g, const Sched& S, const Epi& E) {
;     ...
;         const bool has_next = S.next(ui + 1, nxt);
;         const char* nA = has_next ? (const char*)g.A + (size_t)nxt.pm * tstep : cA; const char* nB = has_next ? (const char*)g.Bt + (size_t)nxt.pn * tstep + (size_t)(nxt.pm >> 5) * g.bstride : cB;
;     ...
; #pragma unroll
;         for (int a = 0; a < 2; ++a)
; #pragma unroll
;             for (int b = 0; b < 2; ++b)
; #pragma unroll
;                 for (int m = 0; m < 4; ++m)
; #pragma unroll
;                     for (int n = 0; n < 2; ++n) acc[a][b][m][n] = (f32x4){0.f, 0.f, 0.f, 0.f};
;         cur = nxt; cA = nA; cB = nB; ++ui;
.LBB0_129:
	s_ashr_i32 s55, s54, 31
	s_lshl_b64 s[26:27], s[54:55], 19
	v_readlane_b32 s60, v251, 16
	v_readlane_b32 s61, v251, 17
	s_add_u32 s58, s60, s26
	s_addc_u32 s59, s61, s27
	s_and_b64 s[4:5], s[4:5], exec
	s_cselect_b32 s26, s59, s3
	s_cselect_b32 s27, s58, s2
	s_add_u32 s2, s2, 0x40080
	s_addc_u32 s3, s3, 0
	s_add_u32 s38, s24, 0x100
	v_mov_b32_e32 v0, 0
	s_addc_u32 s39, s25, 0
	s_mov_b32 s41, -2
	v_mov_b32_e32 v1, v0
	v_mov_b32_e32 v2, v0
	v_mov_b32_e32 v3, v0
	v_mov_b32_e32 v4, v0
	v_mov_b32_e32 v5, v0
	v_mov_b32_e32 v6, v0
	v_mov_b32_e32 v7, v0
	v_mov_b32_e32 v16, v0
	v_mov_b32_e32 v17, v0
	v_mov_b32_e32 v18, v0
	v_mov_b32_e32 v19, v0
	v_mov_b32_e32 v20, v0
	v_mov_b32_e32 v21, v0
	v_mov_b32_e32 v22, v0
	v_mov_b32_e32 v23, v0
	v_mov_b32_e32 v32, v0
	v_mov_b32_e32 v33, v0
	v_mov_b32_e32 v34, v0
	v_mov_b32_e32 v35, v0
	v_mov_b32_e32 v36, v0
	v_mov_b32_e32 v37, v0
	v_mov_b32_e32 v38, v0
	v_mov_b32_e32 v39, v0
	v_mov_b32_e32 v64, v0
	v_mov_b32_e32 v65, v0
	v_mov_b32_e32 v66, v0
	v_mov_b32_e32 v67, v0
	v_mov_b32_e32 v68, v0
	v_mov_b32_e32 v69, v0
	v_mov_b32_e32 v70, v0
	v_mov_b32_e32 v71, v0
	v_mov_b32_e32 v8, v0
	v_mov_b32_e32 v9, v0
	v_mov_b32_e32 v10, v0
	v_mov_b32_e32 v11, v0
	v_mov_b32_e32 v12, v0
	v_mov_b32_e32 v13, v0
	v_mov_b32_e32 v14, v0
	v_mov_b32_e32 v15, v0
	v_mov_b32_e32 v24, v0
	v_mov_b32_e32 v25, v0
	v_mov_b32_e32 v26, v0
	v_mov_b32_e32 v27, v0
	v_mov_b32_e32 v28, v0
	v_mov_b32_e32 v29, v0
	v_mov_b32_e32 v30, v0
	v_mov_b32_e32 v31, v0
	v_mov_b32_e32 v40, v0
	v_mov_b32_e32 v41, v0
	v_mov_b32_e32 v42, v0
	v_mov_b32_e32 v43, v0
	v_mov_b32_e32 v44, v0
	v_mov_b32_e32 v45, v0
	v_mov_b32_e32 v46, v0
	v_mov_b32_e32 v47, v0
	v_mov_b32_e32 v72, v0
	v_mov_b32_e32 v73, v0
	v_mov_b32_e32 v74, v0
	v_mov_b32_e32 v75, v0
	v_mov_b32_e32 v76, v0
	v_mov_b32_e32 v77, v0
	v_mov_b32_e32 v78, v0
	v_mov_b32_e32 v79, v0
	v_mov_b32_e32 v96, v0
	v_mov_b32_e32 v97, v0
	v_mov_b32_e32 v98, v0
	v_mov_b32_e32 v99, v0
	v_mov_b32_e32 v100, v0
	v_mov_b32_e32 v101, v0
	v_mov_b32_e32 v102, v0
	v_mov_b32_e32 v103, v0
	v_mov_b32_e32 v112, v0
	v_mov_b32_e32 v113, v0
	v_mov_b32_e32 v114, v0
	v_mov_b32_e32 v115, v0
	v_mov_b32_e32 v116, v0
	v_mov_b32_e32 v117, v0
	v_mov_b32_e32 v118, v0
	v_mov_b32_e32 v119, v0
	v_mov_b32_e32 v128, v0
	v_mov_b32_e32 v129, v0
	v_mov_b32_e32 v130, v0
	v_mov_b32_e32 v131, v0
	v_mov_b32_e32 v132, v0
	v_mov_b32_e32 v133, v0
	v_mov_b32_e32 v134, v0
	v_mov_b32_e32 v135, v0
	v_mov_b32_e32 v144, v0
	v_mov_b32_e32 v145, v0
	v_mov_b32_e32 v146, v0
	v_mov_b32_e32 v147, v0
	v_mov_b32_e32 v148, v0
	v_mov_b32_e32 v149, v0
	v_mov_b32_e32 v150, v0
	v_mov_b32_e32 v151, v0
	v_mov_b32_e32 v104, v0
	v_mov_b32_e32 v105, v0
	v_mov_b32_e32 v106, v0
	v_mov_b32_e32 v107, v0
	v_mov_b32_e32 v108, v0
	v_mov_b32_e32 v109, v0
	v_mov_b32_e32 v110, v0
	v_mov_b32_e32 v111, v0
	v_mov_b32_e32 v120, v0
	v_mov_b32_e32 v121, v0
	v_mov_b32_e32 v122, v0
	v_mov_b32_e32 v123, v0
	v_mov_b32_e32 v124, v0
	v_mov_b32_e32 v125, v0
	v_mov_b32_e32 v126, v0
	v_mov_b32_e32 v127, v0
	v_mov_b32_e32 v136, v0
	v_mov_b32_e32 v137, v0
	v_mov_b32_e32 v138, v0
	v_mov_b32_e32 v139, v0
	v_mov_b32_e32 v140, v0
	v_mov_b32_e32 v141, v0
	v_mov_b32_e32 v142, v0
	v_mov_b32_e32 v143, v0
	v_mov_b32_e32 v152, v0
	v_mov_b32_e32 v153, v0
	v_mov_b32_e32 v154, v0
	v_mov_b32_e32 v155, v0
	v_mov_b32_e32 v156, v0
	v_mov_b32_e32 v157, v0
	v_mov_b32_e32 v158, v0
	v_mov_b32_e32 v159, v0
	v_readlane_b32 s62, v251, 18
	v_readlane_b32 s63, v251, 19

; template <class Epi, class Sched, bool ALIGN_EPI = false, bool SP2 = false>
; __device__ __forceinline__ void gemm_phase(PG8_LAS unsigned char* lds, const int tid, const Gemm g, const Sched& S, const Epi& E) {
;     ...
;         const bool has_next = S.next(ui + 1, nxt);
;         const char* nA = has_next ? (const char*)g.A + (size_t)nxt.pm * tstep : cA; const char* nB = has_next ? (const char*)g.Bt + (size_t)nxt.pn * tstep + (size_t)(nxt.pm >> 5) * g.bstride : cB;
;     ...
; #pragma unroll
;         for (int a = 0; a < 2; ++a)
; #pragma unroll
;             for (int b = 0; b < 2; ++b)
; #pragma unroll
;                 for (int m = 0; m < 4; ++m)
; #pragma unroll
;                     for (int n = 0; n < 2; ++n) acc[a][b][m][n] = (f32x4){0.f, 0.f, 0.f, 0.f};
;         cur = nxt; cA = nA; cB = nB; ++ui;
.LBB0_310:
	s_add_u32 s38, s26, 0x80
	s_addc_u32 s39, s27, 0
	s_add_u32 s26, s24, 0x100
	v_mov_b32_e32 v0, 0
	s_addc_u32 s27, s25, 0
	s_mov_b32 s14, 0
	s_waitcnt lgkmcnt(0)
	v_mov_b32_e32 v1, v0
	v_mov_b32_e32 v2, v0
	v_mov_b32_e32 v3, v0
	v_mov_b32_e32 v4, v0
	v_mov_b32_e32 v5, v0
	v_mov_b32_e32 v6, v0
	v_mov_b32_e32 v7, v0
	v_mov_b32_e32 v16, v0
	v_mov_b32_e32 v17, v0
	v_mov_b32_e32 v18, v0
	v_mov_b32_e32 v19, v0
	v_mov_b32_e32 v20, v0
	v_mov_b32_e32 v21, v0
	v_mov_b32_e32 v22, v0
	v_mov_b32_e32 v23, v0
	v_mov_b32_e32 v32, v0
	v_mov_b32_e32 v33, v0
	v_mov_b32_e32 v34, v0
	v_mov_b32_e32 v35, v0
	v_mov_b32_e32 v36, v0
	v_mov_b32_e32 v37, v0
	v_mov_b32_e32 v38, v0
	v_mov_b32_e32 v39, v0
	v_mov_b32_e32 v48, v0
	v_mov_b32_e32 v49, v0
	v_mov_b32_e32 v50, v0
	v_mov_b32_e32 v51, v0
	v_mov_b32_e32 v52, v0
	v_mov_b32_e32 v53, v0
	v_mov_b32_e32 v54, v0
	v_mov_b32_e32 v55, v0
	v_mov_b32_e32 v8, v0
	v_mov_b32_e32 v9, v0
	v_mov_b32_e32 v10, v0
	v_mov_b32_e32 v11, v0
	v_mov_b32_e32 v12, v0
	v_mov_b32_e32 v13, v0
	v_mov_b32_e32 v14, v0
	v_mov_b32_e32 v15, v0
	v_mov_b32_e32 v24, v0
	v_mov_b32_e32 v25, v0
	v_mov_b32_e32 v26, v0
	v_mov_b32_e32 v27, v0
	v_mov_b32_e32 v28, v0
	v_mov_b32_e32 v29, v0
	v_mov_b32_e32 v30, v0
	v_mov_b32_e32 v31, v0
	v_mov_b32_e32 v40, v0
	v_mov_b32_e32 v41, v0
	v_mov_b32_e32 v42, v0
	v_mov_b32_e32 v43, v0
	v_mov_b32_e32 v44, v0
	v_mov_b32_e32 v45, v0
	v_mov_b32_e32 v46, v0
	v_mov_b32_e32 v47, v0
	v_mov_b32_e32 v56, v0
	v_mov_b32_e32 v57, v0
	v_mov_b32_e32 v58, v0
	v_mov_b32_e32 v59, v0
	v_mov_b32_e32 v60, v0
	v_mov_b32_e32 v61, v0
	v_mov_b32_e32 v62, v0
	v_mov_b32_e32 v63, v0
	v_mov_b32_e32 v64, v0
	v_mov_b32_e32 v65, v0
	v_mov_b32_e32 v66, v0
	v_mov_b32_e32 v67, v0
	v_mov_b32_e32 v68, v0
	v_mov_b32_e32 v69, v0
	v_mov_b32_e32 v70, v0
	v_mov_b32_e32 v71, v0
	v_mov_b32_e32 v88, v0
	v_mov_b32_e32 v89, v0
	v_mov_b32_e32 v90, v0
	v_mov_b32_e32 v91, v0
	v_mov_b32_e32 v92, v0
	v_mov_b32_e32 v93, v0
	v_mov_b32_e32 v94, v0
	v_mov_b32_e32 v95, v0
	v_mov_b32_e32 v104, v0
	v_mov_b32_e32 v105, v0
	v_mov_b32_e32 v106, v0
	v_mov_b32_e32 v107, v0
	v_mov_b32_e32 v108, v0
	v_mov_b32_e32 v109, v0
	v_mov_b32_e32 v110, v0
	v_mov_b32_e32 v111, v0
	v_mov_b32_e32 v120, v0
	v_mov_b32_e32 v121, v0
	v_mov_b32_e32 v122, v0
	v_mov_b32_e32 v123, v0
	v_mov_b32_e32 v124, v0
	v_mov_b32_e32 v125, v0
	v_mov_b32_e32 v126, v0
	v_mov_b32_e32 v127, v0
	v_mov_b32_e32 v80, v0
	v_mov_b32_e32 v81, v0
	v_mov_b32_e32 v82, v0
	v_mov_b32_e32 v83, v0
	v_mov_b32_e32 v84, v0
	v_mov_b32_e32 v85, v0
	v_mov_b32_e32 v86, v0
	v_mov_b32_e32 v87, v0
	v_mov_b32_e32 v96, v0
	v_mov_b32_e32 v97, v0
	v_mov_b32_e32 v98, v0
	v_mov_b32_e32 v99, v0
	v_mov_b32_e32 v100, v0
	v_mov_b32_e32 v101, v0
	v_mov_b32_e32 v102, v0
	v_mov_b32_e32 v103, v0
	v_mov_b32_e32 v112, v0
	v_mov_b32_e32 v113, v0
	v_mov_b32_e32 v114, v0
	v_mov_b32_e32 v115, v0
	v_mov_b32_e32 v116, v0
	v_mov_b32_e32 v117, v0
	v_mov_b32_e32 v118, v0
	v_mov_b32_e32 v119, v0
	v_mov_b32_e32 v128, v0
	v_mov_b32_e32 v129, v0
	v_mov_b32_e32 v130, v0
	v_mov_b32_e32 v131, v0
	v_mov_b32_e32 v132, v0
	v_mov_b32_e32 v133, v0
	v_mov_b32_e32 v134, v0
	v_mov_b32_e32 v135, v0

; template <class Epi, class Sched, bool ALIGN_EPI = false, bool SP2 = false>
; __device__ __forceinline__ void gemm_phase(PG8_LAS unsigned char* lds, const int tid, const Gemm g, const Sched& S, const Epi& E) {
;     ...
;         const bool has_next = S.next(ui + 1, nxt);
;         const char* nA = has_next ? (const char*)g.A + (size_t)nxt.pm * tstep : cA; const char* nB = has_next ? (const char*)g.Bt + (size_t)nxt.pn * tstep + (size_t)(nxt.pm >> 5) * g.bstride : cB;
;     ...
; #pragma unroll
;         for (int a = 0; a < 2; ++a)
; #pragma unroll
;             for (int b = 0; b < 2; ++b)
; #pragma unroll
;                 for (int m = 0; m < 4; ++m)
; #pragma unroll
;                     for (int n = 0; n < 2; ++n) acc[a][b][m][n] = (f32x4){0.f, 0.f, 0.f, 0.f};
;         cur = nxt; cA = nA; cB = nB; ++ui;
.LBB0_425:
	s_ashr_i32 s41, s40, 31
	s_lshl_b64 s[44:45], s[40:41], 19
	v_readlane_b32 s48, v251, 16
	v_readlane_b32 s49, v251, 17
	s_add_u32 s44, s48, s44
	s_addc_u32 s45, s49, s45
	s_and_b64 s[4:5], s[4:5], exec
	s_cselect_b32 s39, s45, s27
	s_cselect_b32 s41, s44, s26
	s_add_u32 s4, s26, 0x40080
	s_addc_u32 s5, s27, 0
	s_add_u32 s46, s24, 0x100
	v_mov_b32_e32 v0, 0
	s_addc_u32 s47, s25, 0
	s_mov_b32 s48, -2
	v_mov_b32_e32 v1, v0
	v_mov_b32_e32 v2, v0
	v_mov_b32_e32 v3, v0
	v_mov_b32_e32 v4, v0
	v_mov_b32_e32 v5, v0
	v_mov_b32_e32 v6, v0
	v_mov_b32_e32 v7, v0
	v_mov_b32_e32 v16, v0
	v_mov_b32_e32 v17, v0
	v_mov_b32_e32 v18, v0
	v_mov_b32_e32 v19, v0
	v_mov_b32_e32 v20, v0
	v_mov_b32_e32 v21, v0
	v_mov_b32_e32 v22, v0
	v_mov_b32_e32 v23, v0
	v_mov_b32_e32 v32, v0
	v_mov_b32_e32 v33, v0
	v_mov_b32_e32 v34, v0
	v_mov_b32_e32 v35, v0
	v_mov_b32_e32 v36, v0
	v_mov_b32_e32 v37, v0
	v_mov_b32_e32 v38, v0
	v_mov_b32_e32 v39, v0
	v_mov_b32_e32 v48, v0
	v_mov_b32_e32 v49, v0
	v_mov_b32_e32 v50, v0
	v_mov_b32_e32 v51, v0
	v_mov_b32_e32 v52, v0
	v_mov_b32_e32 v53, v0
	v_mov_b32_e32 v54, v0
	v_mov_b32_e32 v55, v0
	v_mov_b32_e32 v8, v0
	v_mov_b32_e32 v9, v0
	v_mov_b32_e32 v10, v0
	v_mov_b32_e32 v11, v0
	v_mov_b32_e32 v12, v0
	v_mov_b32_e32 v13, v0
	v_mov_b32_e32 v14, v0
	v_mov_b32_e32 v15, v0
	v_mov_b32_e32 v24, v0
	v_mov_b32_e32 v25, v0
	v_mov_b32_e32 v26, v0
	v_mov_b32_e32 v27, v0
	v_mov_b32_e32 v28, v0
	v_mov_b32_e32 v29, v0
	v_mov_b32_e32 v30, v0
	v_mov_b32_e32 v31, v0
	v_mov_b32_e32 v40, v0
	v_mov_b32_e32 v41, v0
	v_mov_b32_e32 v42, v0
	v_mov_b32_e32 v43, v0
	v_mov_b32_e32 v44, v0
	v_mov_b32_e32 v45, v0
	v_mov_b32_e32 v46, v0
	v_mov_b32_e32 v47, v0
	v_mov_b32_e32 v56, v0
	v_mov_b32_e32 v57, v0
	v_mov_b32_e32 v58, v0
	v_mov_b32_e32 v59, v0
	v_mov_b32_e32 v60, v0
	v_mov_b32_e32 v61, v0
	v_mov_b32_e32 v62, v0
	v_mov_b32_e32 v63, v0
	v_mov_b32_e32 v80, v0
	v_mov_b32_e32 v81, v0
	v_mov_b32_e32 v82, v0
	v_mov_b32_e32 v83, v0
	v_mov_b32_e32 v84, v0
	v_mov_b32_e32 v85, v0
	v_mov_b32_e32 v86, v0
	v_mov_b32_e32 v87, v0
	v_mov_b32_e32 v96, v0
	v_mov_b32_e32 v97, v0
	v_mov_b32_e32 v98, v0
	v_mov_b32_e32 v99, v0
	v_mov_b32_e32 v100, v0
	v_mov_b32_e32 v101, v0
	v_mov_b32_e32 v102, v0
	v_mov_b32_e32 v103, v0
	v_mov_b32_e32 v112, v0
	v_mov_b32_e32 v113, v0
	v_mov_b32_e32 v114, v0
	v_mov_b32_e32 v115, v0
	v_mov_b32_e32 v116, v0
	v_mov_b32_e32 v117, v0
	v_mov_b32_e32 v118, v0
	v_mov_b32_e32 v119, v0
	v_mov_b32_e32 v128, v0
	v_mov_b32_e32 v129, v0
	v_mov_b32_e32 v130, v0
	v_mov_b32_e32 v131, v0
	v_mov_b32_e32 v132, v0
	v_mov_b32_e32 v133, v0
	v_mov_b32_e32 v134, v0
	v_mov_b32_e32 v135, v0
	v_mov_b32_e32 v88, v0
	v_mov_b32_e32 v89, v0
	v_mov_b32_e32 v90, v0
	v_mov_b32_e32 v91, v0
	v_mov_b32_e32 v92, v0
	v_mov_b32_e32 v93, v0
	v_mov_b32_e32 v94, v0
	v_mov_b32_e32 v95, v0
	v_mov_b32_e32 v104, v0
	v_mov_b32_e32 v105, v0
	v_mov_b32_e32 v106, v0
	v_mov_b32_e32 v107, v0
	v_mov_b32_e32 v108, v0
	v_mov_b32_e32 v109, v0
	v_mov_b32_e32 v110, v0
	v_mov_b32_e32 v111, v0
	v_mov_b32_e32 v120, v0
	v_mov_b32_e32 v121, v0
	v_mov_b32_e32 v122, v0
	v_mov_b32_e32 v123, v0
	v_mov_b32_e32 v124, v0
	v_mov_b32_e32 v125, v0
	v_mov_b32_e32 v126, v0
	v_mov_b32_e32 v127, v0
	v_mov_b32_e32 v136, v0
	v_mov_b32_e32 v137, v0
	v_mov_b32_e32 v138, v0
	v_mov_b32_e32 v139, v0
	v_mov_b32_e32 v140, v0
	v_mov_b32_e32 v141, v0
	v_mov_b32_e32 v142, v0
	v_mov_b32_e32 v143, v0
	v_readlane_b32 s50, v251, 18
	v_readlane_b32 s51, v251, 19
